# v8 + DA attention sub-LN epilogue: 16 gain loads issued up front into dead accumulator registers, stores no longer wait (both grid-256 copies)
# baseline (speedup 1.0000x reference)
.LBB0_728:
	s_mov_b64 s[6:7], 0
	s_cbranch_execz .LBB0_730
	v_mul_f32_e32 v0, v81, v81
	v_fmac_f32_e32 v0, v80, v80
	v_fmac_f32_e32 v0, v82, v82
	v_fmac_f32_e32 v0, v83, v83
	v_fmac_f32_e32 v0, v84, v84
	v_fmac_f32_e32 v0, v85, v85
	v_fmac_f32_e32 v0, v86, v86
	v_fmac_f32_e32 v0, v87, v87
	v_fmac_f32_e32 v0, v88, v88
	v_fmac_f32_e32 v0, v89, v89
	v_fmac_f32_e32 v0, v90, v90
	v_fmac_f32_e32 v0, v91, v91
	v_fmac_f32_e32 v0, v92, v92
	v_fmac_f32_e32 v0, v93, v93
	v_fmac_f32_e32 v0, v94, v94
	v_fmac_f32_e32 v0, v95, v95
	v_fmac_f32_e32 v0, v96, v96
	v_fmac_f32_e32 v0, v97, v97
	v_fmac_f32_e32 v0, v98, v98
	v_fmac_f32_e32 v0, v99, v99
	v_fmac_f32_e32 v0, v100, v100
	v_fmac_f32_e32 v0, v101, v101
	v_fmac_f32_e32 v0, v102, v102
	v_fmac_f32_e32 v0, v103, v103
	v_fmac_f32_e32 v0, v104, v104
	v_fmac_f32_e32 v0, v105, v105
	v_fmac_f32_e32 v0, v106, v106
	v_fmac_f32_e32 v0, v107, v107
	v_fmac_f32_e32 v0, v108, v108
	v_fmac_f32_e32 v0, v109, v109
	v_fmac_f32_e32 v0, v110, v110
	v_fmac_f32_e32 v0, v111, v111
	v_fmac_f32_e32 v0, v112, v112
	v_fmac_f32_e32 v0, v113, v113
	v_fmac_f32_e32 v0, v114, v114
	v_fmac_f32_e32 v0, v115, v115
	v_fmac_f32_e32 v0, v116, v116
	v_fmac_f32_e32 v0, v117, v117
	v_fmac_f32_e32 v0, v118, v118
	v_fmac_f32_e32 v0, v119, v119
	v_fmac_f32_e32 v0, v120, v120
	v_fmac_f32_e32 v0, v121, v121
	v_fmac_f32_e32 v0, v122, v122
	v_fmac_f32_e32 v0, v123, v123
	v_fmac_f32_e32 v0, v124, v124
	v_fmac_f32_e32 v0, v125, v125
	v_fmac_f32_e32 v0, v126, v126
	v_fmac_f32_e32 v0, v127, v127
	v_fmac_f32_e32 v0, v128, v128
	v_fmac_f32_e32 v0, v129, v129
	v_fmac_f32_e32 v0, v130, v130
	v_fmac_f32_e32 v0, v131, v131
	v_fmac_f32_e32 v0, v132, v132
	v_fmac_f32_e32 v0, v133, v133
	v_pk_mul_f32 v[10:11], v[134:135], v[134:135]
	v_pk_mul_f32 v[8:9], v[136:137], v[136:137]
	v_add_f32_e32 v0, v10, v0
	v_add_f32_e32 v0, v11, v0
	v_add_f32_e32 v0, v8, v0
	v_pk_mul_f32 v[6:7], v[138:139], v[138:139]
	v_add_f32_e32 v0, v9, v0
	v_add_f32_e32 v0, v6, v0
	v_pk_mul_f32 v[4:5], v[140:141], v[140:141]
	v_add_f32_e32 v0, v7, v0
	v_add_f32_e32 v0, v4, v0
	v_pk_mul_f32 v[2:3], v[142:143], v[142:143]
	v_add_f32_e32 v0, v5, v0
	v_add_f32_e32 v0, v2, v0
	v_add_f32_e32 v0, v3, v0
	ds_bpermute_b32 v2, v210, v0
	v_and_b32_e32 v185, 31, v240
	v_lshrrev_b32_e32 v184, 5, v194
	v_mov_b32_e32 v12, v184
	v_mov_b32_e32 v13, v185
	s_waitcnt lgkmcnt(0)
	v_add_f32_e32 v0, v0, v2
	v_fmamk_f32 v0, v0, 0x3c000000, v213
	v_cmp_gt_f32_e32 vcc, s79, v0
	v_mul_f32_e32 v2, 0x4b800000, v0
	s_load_dwordx2 s[8:9], s[48:49], 0x88
	v_cndmask_b32_e32 v0, v0, v2, vcc
	v_rsq_f32_e32 v0, v0
	v_readlane_b32 s5, v255, 1
	s_lshl_b32 s5, s5, 2
	s_waitcnt lgkmcnt(0)
	s_add_u32 s8, s8, s5
	v_mul_f32_e32 v2, 0x45800000, v0
	v_cndmask_b32_e32 v0, v0, v2, vcc
	v_add_u32_e32 v2, s4, v13
	v_ashrrev_i32_e32 v3, 31, v2
	v_lshlrev_b32_e32 v10, 2, v12
	s_addc_u32 s9, s9, 0
	v_lshlrev_b64 v[2:3], 11, v[2:3]
	v_readlane_b32 s4, v252, 26
	v_ashrrev_i32_e32 v11, 31, v10
	v_lshl_add_u64 v[2:3], s[0:1], 0, v[2:3]
	s_lshl_b32 s4, s4, 1
	s_mov_b32 s5, s56
	v_lshl_add_u64 v[6:7], v[10:11], 2, s[8:9]
	v_lshl_add_u64 v[8:9], v[2:3], 0, s[4:5]
	global_load_dwordx4 v[16:19], v[6:7], off
	global_load_dwordx4 v[20:23], v[6:7], off offset:32
	global_load_dwordx4 v[24:27], v[6:7], off offset:64
	global_load_dwordx4 v[28:31], v[6:7], off offset:96
	global_load_dwordx4 v[32:35], v[6:7], off offset:128
	global_load_dwordx4 v[36:39], v[6:7], off offset:160
	global_load_dwordx4 v[40:43], v[6:7], off offset:192
	global_load_dwordx4 v[44:47], v[6:7], off offset:224
	global_load_dwordx4 v[48:51], v[6:7], off offset:256
	global_load_dwordx4 v[52:55], v[6:7], off offset:288
	global_load_dwordx4 v[56:59], v[6:7], off offset:320
	global_load_dwordx4 v[60:63], v[6:7], off offset:352
	global_load_dwordx4 v[64:67], v[6:7], off offset:384
	global_load_dwordx4 v[68:71], v[6:7], off offset:416
	global_load_dwordx4 v[72:75], v[6:7], off offset:448
	global_load_dwordx4 v[76:79], v[6:7], off offset:480
	v_mul_f32_e32 v0, v239, v0
	v_pk_mul_f32 v[12:13], v[80:81], v[0:1] op_sel_hi:[1,0]
	s_waitcnt vmcnt(0)
	v_mov_b32_e32 v2, v16
	v_mov_b32_e32 v3, v17
	v_mov_b32_e32 v4, v18
	v_mov_b32_e32 v5, v19
	v_pk_mul_f32 v[2:3], v[2:3], v[12:13]
	s_nop 0
	v_cvt_pk_bf16_f32 v12, v2, v3
	v_pk_mul_f32 v[2:3], v[82:83], v[0:1] op_sel_hi:[1,0]
	s_nop 0
	v_pk_mul_f32 v[2:3], v[4:5], v[2:3]
	v_pk_mul_f32 v[4:5], v[84:85], v[0:1] op_sel_hi:[1,0]
	v_cvt_pk_bf16_f32 v13, v2, v3
	v_lshl_add_u64 v[2:3], v[10:11], 1, v[8:9]
	global_store_dwordx2 v[2:3], v[12:13], off
	v_mov_b32_e32 v8, v20
	v_mov_b32_e32 v9, v21
	v_mov_b32_e32 v10, v22
	v_mov_b32_e32 v11, v23
	v_pk_mul_f32 v[4:5], v[8:9], v[4:5]
	v_pk_mul_f32 v[8:9], v[86:87], v[0:1] op_sel_hi:[1,0]
	v_cvt_pk_bf16_f32 v4, v4, v5
	v_pk_mul_f32 v[8:9], v[10:11], v[8:9]
	s_nop 0
	v_cvt_pk_bf16_f32 v5, v8, v9
	global_store_dwordx2 v[2:3], v[4:5], off offset:16
	v_pk_mul_f32 v[4:5], v[88:89], v[0:1] op_sel_hi:[1,0]
	v_mov_b32_e32 v8, v24
	v_mov_b32_e32 v9, v25
	v_mov_b32_e32 v10, v26
	v_mov_b32_e32 v11, v27
	v_pk_mul_f32 v[4:5], v[8:9], v[4:5]
	v_pk_mul_f32 v[8:9], v[90:91], v[0:1] op_sel_hi:[1,0]
	v_cvt_pk_bf16_f32 v4, v4, v5
	v_pk_mul_f32 v[8:9], v[10:11], v[8:9]
	s_nop 0
	v_cvt_pk_bf16_f32 v5, v8, v9
	global_store_dwordx2 v[2:3], v[4:5], off offset:32
	v_pk_mul_f32 v[4:5], v[92:93], v[0:1] op_sel_hi:[1,0]
	v_mov_b32_e32 v8, v28
	v_mov_b32_e32 v9, v29
	v_mov_b32_e32 v10, v30
	v_mov_b32_e32 v11, v31
	v_pk_mul_f32 v[4:5], v[8:9], v[4:5]
	v_pk_mul_f32 v[8:9], v[94:95], v[0:1] op_sel_hi:[1,0]
	v_cvt_pk_bf16_f32 v4, v4, v5
	v_pk_mul_f32 v[8:9], v[10:11], v[8:9]
	s_nop 0
	v_cvt_pk_bf16_f32 v5, v8, v9
	global_store_dwordx2 v[2:3], v[4:5], off offset:48
	v_pk_mul_f32 v[4:5], v[96:97], v[0:1] op_sel_hi:[1,0]
	v_mov_b32_e32 v8, v32
	v_mov_b32_e32 v9, v33
	v_mov_b32_e32 v10, v34
	v_mov_b32_e32 v11, v35
	v_pk_mul_f32 v[4:5], v[8:9], v[4:5]
	v_pk_mul_f32 v[8:9], v[98:99], v[0:1] op_sel_hi:[1,0]
	v_cvt_pk_bf16_f32 v4, v4, v5
	v_pk_mul_f32 v[8:9], v[10:11], v[8:9]
	s_nop 0
	v_cvt_pk_bf16_f32 v5, v8, v9
	global_store_dwordx2 v[2:3], v[4:5], off offset:64
	v_pk_mul_f32 v[4:5], v[100:101], v[0:1] op_sel_hi:[1,0]
	v_mov_b32_e32 v8, v36
	v_mov_b32_e32 v9, v37
	v_mov_b32_e32 v10, v38
	v_mov_b32_e32 v11, v39
	v_pk_mul_f32 v[4:5], v[8:9], v[4:5]
	v_pk_mul_f32 v[8:9], v[102:103], v[0:1] op_sel_hi:[1,0]
	v_cvt_pk_bf16_f32 v4, v4, v5
	v_pk_mul_f32 v[8:9], v[10:11], v[8:9]
	s_nop 0
	v_cvt_pk_bf16_f32 v5, v8, v9
	global_store_dwordx2 v[2:3], v[4:5], off offset:80
	v_pk_mul_f32 v[4:5], v[104:105], v[0:1] op_sel_hi:[1,0]
	v_mov_b32_e32 v8, v40
	v_mov_b32_e32 v9, v41
	v_mov_b32_e32 v10, v42
	v_mov_b32_e32 v11, v43
	v_pk_mul_f32 v[4:5], v[8:9], v[4:5]
	v_pk_mul_f32 v[8:9], v[106:107], v[0:1] op_sel_hi:[1,0]
	v_cvt_pk_bf16_f32 v4, v4, v5
	v_pk_mul_f32 v[8:9], v[10:11], v[8:9]
	s_nop 0
	v_cvt_pk_bf16_f32 v5, v8, v9
	global_store_dwordx2 v[2:3], v[4:5], off offset:96
	v_pk_mul_f32 v[4:5], v[108:109], v[0:1] op_sel_hi:[1,0]
	v_mov_b32_e32 v8, v44
	v_mov_b32_e32 v9, v45
	v_mov_b32_e32 v10, v46
	v_mov_b32_e32 v11, v47
	v_pk_mul_f32 v[4:5], v[8:9], v[4:5]
	v_pk_mul_f32 v[8:9], v[110:111], v[0:1] op_sel_hi:[1,0]
	v_cvt_pk_bf16_f32 v4, v4, v5
	v_pk_mul_f32 v[8:9], v[10:11], v[8:9]
	s_nop 0
	v_cvt_pk_bf16_f32 v5, v8, v9
	global_store_dwordx2 v[2:3], v[4:5], off offset:112
	v_pk_mul_f32 v[4:5], v[112:113], v[0:1] op_sel_hi:[1,0]
	v_mov_b32_e32 v8, v48
	v_mov_b32_e32 v9, v49
	v_mov_b32_e32 v10, v50
	v_mov_b32_e32 v11, v51
	v_pk_mul_f32 v[4:5], v[8:9], v[4:5]
	v_pk_mul_f32 v[8:9], v[114:115], v[0:1] op_sel_hi:[1,0]
	v_cvt_pk_bf16_f32 v4, v4, v5
	v_pk_mul_f32 v[8:9], v[10:11], v[8:9]
	s_nop 0
	v_cvt_pk_bf16_f32 v5, v8, v9
	global_store_dwordx2 v[2:3], v[4:5], off offset:128
	v_pk_mul_f32 v[4:5], v[116:117], v[0:1] op_sel_hi:[1,0]
	v_mov_b32_e32 v8, v52
	v_mov_b32_e32 v9, v53
	v_mov_b32_e32 v10, v54
	v_mov_b32_e32 v11, v55
	v_pk_mul_f32 v[4:5], v[8:9], v[4:5]
	v_pk_mul_f32 v[8:9], v[118:119], v[0:1] op_sel_hi:[1,0]
	v_cvt_pk_bf16_f32 v4, v4, v5
	v_pk_mul_f32 v[8:9], v[10:11], v[8:9]
	s_nop 0
	v_cvt_pk_bf16_f32 v5, v8, v9
	global_store_dwordx2 v[2:3], v[4:5], off offset:144
	v_pk_mul_f32 v[4:5], v[120:121], v[0:1] op_sel_hi:[1,0]
	v_mov_b32_e32 v8, v56
	v_mov_b32_e32 v9, v57
	v_mov_b32_e32 v10, v58
	v_mov_b32_e32 v11, v59
	v_pk_mul_f32 v[4:5], v[8:9], v[4:5]
	v_pk_mul_f32 v[8:9], v[122:123], v[0:1] op_sel_hi:[1,0]
	v_cvt_pk_bf16_f32 v4, v4, v5
	v_pk_mul_f32 v[8:9], v[10:11], v[8:9]
	s_nop 0
	v_cvt_pk_bf16_f32 v5, v8, v9
	global_store_dwordx2 v[2:3], v[4:5], off offset:160
	v_pk_mul_f32 v[4:5], v[124:125], v[0:1] op_sel_hi:[1,0]
	v_mov_b32_e32 v8, v60
	v_mov_b32_e32 v9, v61
	v_mov_b32_e32 v10, v62
	v_mov_b32_e32 v11, v63
	v_pk_mul_f32 v[4:5], v[8:9], v[4:5]
	v_pk_mul_f32 v[8:9], v[126:127], v[0:1] op_sel_hi:[1,0]
	v_cvt_pk_bf16_f32 v4, v4, v5
	v_pk_mul_f32 v[8:9], v[10:11], v[8:9]
	s_nop 0
	v_cvt_pk_bf16_f32 v5, v8, v9
	global_store_dwordx2 v[2:3], v[4:5], off offset:176
	v_pk_mul_f32 v[4:5], v[128:129], v[0:1] op_sel_hi:[1,0]
	v_mov_b32_e32 v8, v64
	v_mov_b32_e32 v9, v65
	v_mov_b32_e32 v10, v66
	v_mov_b32_e32 v11, v67
	v_pk_mul_f32 v[4:5], v[8:9], v[4:5]
	v_pk_mul_f32 v[8:9], v[130:131], v[0:1] op_sel_hi:[1,0]
	v_cvt_pk_bf16_f32 v4, v4, v5
	v_pk_mul_f32 v[8:9], v[10:11], v[8:9]
	s_nop 0
	v_cvt_pk_bf16_f32 v5, v8, v9
	global_store_dwordx2 v[2:3], v[4:5], off offset:192
	v_pk_mul_f32 v[4:5], v[132:133], v[0:1] op_sel_hi:[1,0]
	v_mov_b32_e32 v8, v68
	v_mov_b32_e32 v9, v69
	v_mov_b32_e32 v10, v70
	v_mov_b32_e32 v11, v71
	v_pk_mul_f32 v[4:5], v[8:9], v[4:5]
	v_pk_mul_f32 v[8:9], v[134:135], v[0:1] op_sel_hi:[1,0]
	v_cvt_pk_bf16_f32 v4, v4, v5
	v_pk_mul_f32 v[8:9], v[10:11], v[8:9]
	s_nop 0
	v_cvt_pk_bf16_f32 v5, v8, v9
	global_store_dwordx2 v[2:3], v[4:5], off offset:208
	v_pk_mul_f32 v[4:5], v[136:137], v[0:1] op_sel_hi:[1,0]
	v_mov_b32_e32 v8, v72
	v_mov_b32_e32 v9, v73
	v_mov_b32_e32 v10, v74
	v_mov_b32_e32 v11, v75
	v_pk_mul_f32 v[4:5], v[8:9], v[4:5]
	v_pk_mul_f32 v[8:9], v[138:139], v[0:1] op_sel_hi:[1,0]
	v_cvt_pk_bf16_f32 v4, v4, v5
	v_pk_mul_f32 v[8:9], v[10:11], v[8:9]
	s_nop 0
	v_cvt_pk_bf16_f32 v5, v8, v9
	global_store_dwordx2 v[2:3], v[4:5], off offset:224
	v_pk_mul_f32 v[8:9], v[140:141], v[0:1] op_sel_hi:[1,0]
	v_mov_b32_e32 v4, v76
	v_mov_b32_e32 v5, v77
	v_mov_b32_e32 v6, v78
	v_mov_b32_e32 v7, v79
	v_pk_mul_f32 v[4:5], v[4:5], v[8:9]
	v_pk_mul_f32 v[8:9], v[142:143], v[0:1] op_sel_hi:[1,0]
	v_cvt_pk_bf16_f32 v4, v4, v5
	v_pk_mul_f32 v[6:7], v[6:7], v[8:9]
	s_nop 0
	v_cvt_pk_bf16_f32 v5, v6, v7
	global_store_dwordx2 v[2:3], v[4:5], off offset:240

.LBB0_744:
	v_mul_f32_e32 v0, v129, v129
	v_fmac_f32_e32 v0, v128, v128
	v_fmac_f32_e32 v0, v130, v130
	v_fmac_f32_e32 v0, v131, v131
	v_fmac_f32_e32 v0, v132, v132
	v_fmac_f32_e32 v0, v133, v133
	v_fmac_f32_e32 v0, v134, v134
	v_fmac_f32_e32 v0, v135, v135
	v_fmac_f32_e32 v0, v136, v136
	v_fmac_f32_e32 v0, v137, v137
	v_fmac_f32_e32 v0, v138, v138
	v_fmac_f32_e32 v0, v139, v139
	v_fmac_f32_e32 v0, v140, v140
	v_fmac_f32_e32 v0, v141, v141
	v_fmac_f32_e32 v0, v142, v142
	v_fmac_f32_e32 v0, v143, v143
	v_fmac_f32_e32 v0, v112, v112
	v_fmac_f32_e32 v0, v113, v113
	v_fmac_f32_e32 v0, v114, v114
	v_fmac_f32_e32 v0, v115, v115
	v_fmac_f32_e32 v0, v116, v116
	v_fmac_f32_e32 v0, v117, v117
	v_fmac_f32_e32 v0, v118, v118
	v_fmac_f32_e32 v0, v119, v119
	v_fmac_f32_e32 v0, v120, v120
	v_fmac_f32_e32 v0, v121, v121
	v_fmac_f32_e32 v0, v122, v122
	v_fmac_f32_e32 v0, v123, v123
	v_fmac_f32_e32 v0, v124, v124
	v_fmac_f32_e32 v0, v125, v125
	v_fmac_f32_e32 v0, v126, v126
	v_fmac_f32_e32 v0, v127, v127
	v_fmac_f32_e32 v0, v96, v96
	v_fmac_f32_e32 v0, v97, v97
	v_fmac_f32_e32 v0, v98, v98
	v_fmac_f32_e32 v0, v99, v99
	v_fmac_f32_e32 v0, v100, v100
	v_fmac_f32_e32 v0, v101, v101
	v_fmac_f32_e32 v0, v102, v102
	v_fmac_f32_e32 v0, v103, v103
	v_fmac_f32_e32 v0, v104, v104
	v_fmac_f32_e32 v0, v105, v105
	v_fmac_f32_e32 v0, v106, v106
	v_fmac_f32_e32 v0, v107, v107
	v_fmac_f32_e32 v0, v108, v108
	v_fmac_f32_e32 v0, v109, v109
	v_fmac_f32_e32 v0, v110, v110
	v_fmac_f32_e32 v0, v111, v111
	v_fmac_f32_e32 v0, v80, v80
	v_fmac_f32_e32 v0, v81, v81
	v_fmac_f32_e32 v0, v82, v82
	v_fmac_f32_e32 v0, v83, v83
	v_fmac_f32_e32 v0, v84, v84
	v_fmac_f32_e32 v0, v85, v85
	v_pk_mul_f32 v[10:11], v[86:87], v[86:87]
	v_pk_mul_f32 v[8:9], v[88:89], v[88:89]
	v_add_f32_e32 v0, v10, v0
	v_add_f32_e32 v0, v11, v0
	v_add_f32_e32 v0, v8, v0
	v_pk_mul_f32 v[6:7], v[90:91], v[90:91]
	v_add_f32_e32 v0, v9, v0
	v_add_f32_e32 v0, v6, v0
	v_pk_mul_f32 v[4:5], v[92:93], v[92:93]
	v_add_f32_e32 v0, v7, v0
	v_add_f32_e32 v0, v4, v0
	v_pk_mul_f32 v[2:3], v[94:95], v[94:95]
	v_add_f32_e32 v0, v5, v0
	v_add_f32_e32 v0, v2, v0
	v_add_f32_e32 v0, v3, v0
	ds_bpermute_b32 v2, v210, v0
	s_load_dwordx2 s[8:9], s[48:49], 0x88
	v_readlane_b32 s5, v255, 1
	s_lshl_b32 s5, s5, 2
	s_waitcnt lgkmcnt(0)
	v_add_f32_e32 v0, v0, v2
	v_fmamk_f32 v0, v0, 0x3c000000, v213
	v_cmp_gt_f32_e32 vcc, s79, v0
	v_mul_f32_e32 v2, 0x4b800000, v0
	s_add_u32 s8, s8, s5
	v_cndmask_b32_e32 v0, v0, v2, vcc
	v_rsq_f32_e32 v0, v0
	v_lshlrev_b32_e32 v10, 2, v184
	s_addc_u32 s9, s9, 0
	v_ashrrev_i32_e32 v11, 31, v10
	v_mul_f32_e32 v2, 0x45800000, v0
	v_cndmask_b32_e32 v0, v0, v2, vcc
	v_add_u32_e32 v2, s4, v185
	v_ashrrev_i32_e32 v3, 31, v2
	v_lshlrev_b64 v[2:3], 11, v[2:3]
	v_lshl_add_u64 v[2:3], s[0:1], 0, v[2:3]
	s_mov_b32 s7, s56
	v_lshl_add_u64 v[6:7], v[10:11], 2, s[8:9]
	v_lshl_add_u64 v[8:9], v[2:3], 0, s[6:7]
	global_load_dwordx4 v[16:19], v[6:7], off
	global_load_dwordx4 v[20:23], v[6:7], off offset:32
	global_load_dwordx4 v[24:27], v[6:7], off offset:64
	global_load_dwordx4 v[28:31], v[6:7], off offset:96
	global_load_dwordx4 v[32:35], v[6:7], off offset:128
	global_load_dwordx4 v[36:39], v[6:7], off offset:160
	global_load_dwordx4 v[40:43], v[6:7], off offset:192
	global_load_dwordx4 v[44:47], v[6:7], off offset:224
	global_load_dwordx4 v[48:51], v[6:7], off offset:256
	global_load_dwordx4 v[52:55], v[6:7], off offset:288
	global_load_dwordx4 v[56:59], v[6:7], off offset:320
	global_load_dwordx4 v[60:63], v[6:7], off offset:352
	global_load_dwordx4 v[64:67], v[6:7], off offset:384
	global_load_dwordx4 v[68:71], v[6:7], off offset:416
	global_load_dwordx4 v[72:75], v[6:7], off offset:448
	global_load_dwordx4 v[76:79], v[6:7], off offset:480
	v_mul_f32_e32 v0, v239, v0
	v_pk_mul_f32 v[12:13], v[128:129], v[0:1] op_sel_hi:[1,0]
	s_waitcnt vmcnt(0)
	v_mov_b32_e32 v2, v16
	v_mov_b32_e32 v3, v17
	v_mov_b32_e32 v4, v18
	v_mov_b32_e32 v5, v19
	v_pk_mul_f32 v[2:3], v[2:3], v[12:13]
	s_nop 0
	v_cvt_pk_bf16_f32 v12, v2, v3
	v_pk_mul_f32 v[2:3], v[130:131], v[0:1] op_sel_hi:[1,0]
	s_nop 0
	v_pk_mul_f32 v[2:3], v[4:5], v[2:3]
	v_pk_mul_f32 v[4:5], v[132:133], v[0:1] op_sel_hi:[1,0]
	v_cvt_pk_bf16_f32 v13, v2, v3
	v_lshl_add_u64 v[2:3], v[10:11], 1, v[8:9]
	global_store_dwordx2 v[2:3], v[12:13], off
	v_mov_b32_e32 v8, v20
	v_mov_b32_e32 v9, v21
	v_mov_b32_e32 v10, v22
	v_mov_b32_e32 v11, v23
	v_pk_mul_f32 v[4:5], v[8:9], v[4:5]
	v_pk_mul_f32 v[8:9], v[134:135], v[0:1] op_sel_hi:[1,0]
	v_cvt_pk_bf16_f32 v4, v4, v5
	v_pk_mul_f32 v[8:9], v[10:11], v[8:9]
	s_nop 0
	v_cvt_pk_bf16_f32 v5, v8, v9
	global_store_dwordx2 v[2:3], v[4:5], off offset:16
	v_pk_mul_f32 v[4:5], v[136:137], v[0:1] op_sel_hi:[1,0]
	v_mov_b32_e32 v8, v24
	v_mov_b32_e32 v9, v25
	v_mov_b32_e32 v10, v26
	v_mov_b32_e32 v11, v27
	v_pk_mul_f32 v[4:5], v[8:9], v[4:5]
	v_pk_mul_f32 v[8:9], v[138:139], v[0:1] op_sel_hi:[1,0]
	v_cvt_pk_bf16_f32 v4, v4, v5
	v_pk_mul_f32 v[8:9], v[10:11], v[8:9]
	s_nop 0
	v_cvt_pk_bf16_f32 v5, v8, v9
	global_store_dwordx2 v[2:3], v[4:5], off offset:32
	v_pk_mul_f32 v[4:5], v[140:141], v[0:1] op_sel_hi:[1,0]
	v_mov_b32_e32 v8, v28
	v_mov_b32_e32 v9, v29
	v_mov_b32_e32 v10, v30
	v_mov_b32_e32 v11, v31
	v_pk_mul_f32 v[4:5], v[8:9], v[4:5]
	v_pk_mul_f32 v[8:9], v[142:143], v[0:1] op_sel_hi:[1,0]
	v_cvt_pk_bf16_f32 v4, v4, v5
	v_pk_mul_f32 v[8:9], v[10:11], v[8:9]
	s_nop 0
	v_cvt_pk_bf16_f32 v5, v8, v9
	global_store_dwordx2 v[2:3], v[4:5], off offset:48
	v_pk_mul_f32 v[4:5], v[112:113], v[0:1] op_sel_hi:[1,0]
	v_mov_b32_e32 v8, v32
	v_mov_b32_e32 v9, v33
	v_mov_b32_e32 v10, v34
	v_mov_b32_e32 v11, v35
	v_pk_mul_f32 v[4:5], v[8:9], v[4:5]
	v_pk_mul_f32 v[8:9], v[114:115], v[0:1] op_sel_hi:[1,0]
	v_cvt_pk_bf16_f32 v4, v4, v5
	v_pk_mul_f32 v[8:9], v[10:11], v[8:9]
	s_nop 0
	v_cvt_pk_bf16_f32 v5, v8, v9
	global_store_dwordx2 v[2:3], v[4:5], off offset:64
	v_pk_mul_f32 v[4:5], v[116:117], v[0:1] op_sel_hi:[1,0]
	v_mov_b32_e32 v8, v36
	v_mov_b32_e32 v9, v37
	v_mov_b32_e32 v10, v38
	v_mov_b32_e32 v11, v39
	v_pk_mul_f32 v[4:5], v[4:5], v[8:9]
	v_pk_mul_f32 v[8:9], v[118:119], v[0:1] op_sel_hi:[1,0]
	v_cvt_pk_bf16_f32 v4, v4, v5
	v_pk_mul_f32 v[8:9], v[8:9], v[10:11]
	s_nop 0
	v_cvt_pk_bf16_f32 v5, v8, v9
	global_store_dwordx2 v[2:3], v[4:5], off offset:80
	v_pk_mul_f32 v[4:5], v[120:121], v[0:1] op_sel_hi:[1,0]
	v_mov_b32_e32 v8, v40
	v_mov_b32_e32 v9, v41
	v_mov_b32_e32 v10, v42
	v_mov_b32_e32 v11, v43
	v_pk_mul_f32 v[4:5], v[4:5], v[8:9]
	v_pk_mul_f32 v[8:9], v[122:123], v[0:1] op_sel_hi:[1,0]
	v_cvt_pk_bf16_f32 v4, v4, v5
	v_pk_mul_f32 v[8:9], v[8:9], v[10:11]
	s_nop 0
	v_cvt_pk_bf16_f32 v5, v8, v9
	global_store_dwordx2 v[2:3], v[4:5], off offset:96
	v_pk_mul_f32 v[4:5], v[124:125], v[0:1] op_sel_hi:[1,0]
	v_mov_b32_e32 v8, v44
	v_mov_b32_e32 v9, v45
	v_mov_b32_e32 v10, v46
	v_mov_b32_e32 v11, v47
	v_pk_mul_f32 v[4:5], v[4:5], v[8:9]
	v_pk_mul_f32 v[8:9], v[126:127], v[0:1] op_sel_hi:[1,0]
	v_cvt_pk_bf16_f32 v4, v4, v5
	v_pk_mul_f32 v[8:9], v[8:9], v[10:11]
	s_nop 0
	v_cvt_pk_bf16_f32 v5, v8, v9
	global_store_dwordx2 v[2:3], v[4:5], off offset:112
	v_pk_mul_f32 v[4:5], v[96:97], v[0:1] op_sel_hi:[1,0]
	v_mov_b32_e32 v8, v48
	v_mov_b32_e32 v9, v49
	v_mov_b32_e32 v10, v50
	v_mov_b32_e32 v11, v51
	v_pk_mul_f32 v[4:5], v[4:5], v[8:9]
	v_pk_mul_f32 v[8:9], v[98:99], v[0:1] op_sel_hi:[1,0]
	v_cvt_pk_bf16_f32 v4, v4, v5
	v_pk_mul_f32 v[8:9], v[8:9], v[10:11]
	s_nop 0
	v_cvt_pk_bf16_f32 v5, v8, v9
	global_store_dwordx2 v[2:3], v[4:5], off offset:128
	v_pk_mul_f32 v[4:5], v[100:101], v[0:1] op_sel_hi:[1,0]
	v_mov_b32_e32 v8, v52
	v_mov_b32_e32 v9, v53
	v_mov_b32_e32 v10, v54
	v_mov_b32_e32 v11, v55
	v_pk_mul_f32 v[4:5], v[4:5], v[8:9]
	v_pk_mul_f32 v[8:9], v[102:103], v[0:1] op_sel_hi:[1,0]
	v_cvt_pk_bf16_f32 v4, v4, v5
	v_pk_mul_f32 v[8:9], v[8:9], v[10:11]
	s_nop 0
	v_cvt_pk_bf16_f32 v5, v8, v9
	global_store_dwordx2 v[2:3], v[4:5], off offset:144
	v_pk_mul_f32 v[4:5], v[104:105], v[0:1] op_sel_hi:[1,0]
	v_mov_b32_e32 v8, v56
	v_mov_b32_e32 v9, v57
	v_mov_b32_e32 v10, v58
	v_mov_b32_e32 v11, v59
	v_pk_mul_f32 v[4:5], v[4:5], v[8:9]
	v_pk_mul_f32 v[8:9], v[106:107], v[0:1] op_sel_hi:[1,0]
	v_cvt_pk_bf16_f32 v4, v4, v5
	v_pk_mul_f32 v[8:9], v[8:9], v[10:11]
	s_nop 0
	v_cvt_pk_bf16_f32 v5, v8, v9
	global_store_dwordx2 v[2:3], v[4:5], off offset:160
	v_pk_mul_f32 v[4:5], v[108:109], v[0:1] op_sel_hi:[1,0]
	v_mov_b32_e32 v8, v60
	v_mov_b32_e32 v9, v61
	v_mov_b32_e32 v10, v62
	v_mov_b32_e32 v11, v63
	v_pk_mul_f32 v[4:5], v[4:5], v[8:9]
	v_pk_mul_f32 v[8:9], v[110:111], v[0:1] op_sel_hi:[1,0]
	v_cvt_pk_bf16_f32 v4, v4, v5
	v_pk_mul_f32 v[8:9], v[8:9], v[10:11]
	s_nop 0
	v_cvt_pk_bf16_f32 v5, v8, v9
	global_store_dwordx2 v[2:3], v[4:5], off offset:176
	v_pk_mul_f32 v[4:5], v[80:81], v[0:1] op_sel_hi:[1,0]
	v_mov_b32_e32 v8, v64
	v_mov_b32_e32 v9, v65
	v_mov_b32_e32 v10, v66
	v_mov_b32_e32 v11, v67
	v_pk_mul_f32 v[4:5], v[4:5], v[8:9]
	v_pk_mul_f32 v[8:9], v[82:83], v[0:1] op_sel_hi:[1,0]
	v_cvt_pk_bf16_f32 v4, v4, v5
	v_pk_mul_f32 v[8:9], v[8:9], v[10:11]
	s_nop 0
	v_cvt_pk_bf16_f32 v5, v8, v9
	global_store_dwordx2 v[2:3], v[4:5], off offset:192
	v_pk_mul_f32 v[4:5], v[84:85], v[0:1] op_sel_hi:[1,0]
	v_mov_b32_e32 v8, v68
	v_mov_b32_e32 v9, v69
	v_mov_b32_e32 v10, v70
	v_mov_b32_e32 v11, v71
	v_pk_mul_f32 v[4:5], v[4:5], v[8:9]
	v_pk_mul_f32 v[8:9], v[86:87], v[0:1] op_sel_hi:[1,0]
	v_cvt_pk_bf16_f32 v4, v4, v5
	v_pk_mul_f32 v[8:9], v[8:9], v[10:11]
	s_nop 0
	v_cvt_pk_bf16_f32 v5, v8, v9
	global_store_dwordx2 v[2:3], v[4:5], off offset:208
	v_pk_mul_f32 v[4:5], v[88:89], v[0:1] op_sel_hi:[1,0]
	v_mov_b32_e32 v8, v72
	v_mov_b32_e32 v9, v73
	v_mov_b32_e32 v10, v74
	v_mov_b32_e32 v11, v75
	v_pk_mul_f32 v[4:5], v[4:5], v[8:9]
	v_pk_mul_f32 v[8:9], v[90:91], v[0:1] op_sel_hi:[1,0]
	v_cvt_pk_bf16_f32 v4, v4, v5
	v_pk_mul_f32 v[8:9], v[8:9], v[10:11]
	s_nop 0
	v_cvt_pk_bf16_f32 v5, v8, v9
	global_store_dwordx2 v[2:3], v[4:5], off offset:224
	v_pk_mul_f32 v[8:9], v[92:93], v[0:1] op_sel_hi:[1,0]
	v_mov_b32_e32 v4, v76
	v_mov_b32_e32 v5, v77
	v_mov_b32_e32 v6, v78
	v_mov_b32_e32 v7, v79
	v_pk_mul_f32 v[4:5], v[8:9], v[4:5]
	v_pk_mul_f32 v[8:9], v[94:95], v[0:1] op_sel_hi:[1,0]
	v_cvt_pk_bf16_f32 v4, v4, v5
	v_pk_mul_f32 v[6:7], v[8:9], v[6:7]
	s_nop 0
	v_cvt_pk_bf16_f32 v5, v6, v7
	global_store_dwordx2 v[2:3], v[4:5], off offset:240
